# attention: skip fully-masked key tiles per wave in the diagonal q-block (drain pending block once, idle to unit end)
# speedup vs baseline: 1.0098x; 1.0098x over previous
.LBB0_1338:
	v_mov_b32_e32 v54, v191
	s_lshl_b32 s97, s4, 8
	s_add_i32 s97, s97, s79
	v_and_b32_e32 v48, 31, v54
	v_or_b32_e32 v0, s97, v48
	v_ashrrev_i32_e32 v50, 3, v54
	v_and_b32_e32 v56, 7, v54
	v_bfe_u32 v49, v54, 5, 1
	v_add_u32_e32 v0, s91, v0
	s_movk_i32 s0, 0xc00
	v_ashrrev_i32_e32 v51, 4, v54
	v_and_b32_e32 v55, 15, v54
	v_add_u32_e32 v9, s91, v50
	v_lshlrev_b32_e32 v52, 3, v56
	v_ashrrev_i32_e32 v1, 31, v0
	v_mad_i64_i32 v[2:3], s[0:1], v0, s0, v[182:183]
	v_lshlrev_b32_e32 v180, 4, v49
	v_add_lshl_u32 v8, v51, s91, 10
	v_lshlrev_b32_e32 v53, 3, v55
	v_lshl_or_b32 v10, v9, 6, v52
	v_add_lshl_u32 v9, v50, s92, 15
	v_lshl_add_u64 v[24:25], v[2:3], 0, v[180:181]
	v_lshlrev_b64 v[0:1], 7, v[0:1]
	v_or3_b32 v8, v8, v53, s92
	v_or3_b32 v12, v9, s91, v52
	v_add_lshl_u32 v234, v50, s92, 11
	v_add_u32_e32 v12, v12, v234
	v_mov_b32_e32 v9, v181
	global_load_dwordx4 v[96:99], v[24:25], off
	global_load_dwordx4 v[100:103], v[24:25], off offset:32
	global_load_dwordx4 v[104:107], v[24:25], off offset:64
	global_load_dwordx4 v[108:111], v[24:25], off offset:96
	global_load_dwordx4 v[112:115], v[24:25], off offset:128
	global_load_dwordx4 v[116:119], v[24:25], off offset:160
	global_load_dwordx4 v[120:123], v[24:25], off offset:192
	global_load_dwordx4 v[124:127], v[24:25], off offset:224
	v_lshl_add_u64 v[2:3], s[62:63], 0, v[0:1]
	v_lshlrev_b32_e32 v4, 5, v49
	v_mov_b32_e32 v5, v181
	v_lshl_add_u64 v[14:15], v[8:9], 1, s[64:65]
	v_add_u32_e32 v8, 0x8000, v8
	v_lshl_add_u64 v[28:29], v[2:3], 0, v[4:5]
	v_lshl_add_u64 v[0:1], s[66:67], 0, v[0:1]
	v_lshl_add_u64 v[8:9], v[8:9], 1, s[64:65]
	v_mov_b32_e32 v11, v181
	v_lshl_add_u64 v[44:45], v[0:1], 0, v[4:5]
	global_load_dwordx4 v[0:3], v[28:29], off offset:16
	global_load_dwordx4 v[4:7], v[28:29], off
	global_load_dwordx4 v[128:131], v[14:15], off
	global_load_dwordx4 v[132:135], v[8:9], off
	v_lshl_add_u64 v[8:9], v[10:11], 1, s[60:61]
	v_mov_b32_e32 v13, v181
	v_lshl_add_u64 v[10:11], v[12:13], 1, s[68:69]
	global_load_dwordx4 v[136:139], v[8:9], off
	global_load_dwordx4 v[140:143], v[10:11], off
	v_add_u32_e32 v8, 0x220000, v12
	v_mov_b32_e32 v9, v181
	v_lshl_add_u64 v[8:9], v[8:9], 1, s[68:69]
	global_load_dwordx4 v[144:147], v[8:9], off
	s_nop 0
	global_load_dwordx4 v[8:11], v[44:45], off offset:16
	global_load_dwordx4 v[20:23], v[44:45], off
	global_load_dwordx4 v[12:15], v[24:25], off offset:256
	global_load_dwordx4 v[32:35], v[24:25], off offset:288
	global_load_dwordx4 v[16:19], v[24:25], off offset:320
	global_load_dwordx4 v[36:39], v[24:25], off offset:352
	s_nop 0
	global_load_dwordx4 v[24:27], v[28:29], off offset:80
	global_load_dwordx4 v[40:43], v[28:29], off offset:64
	s_nop 0
	global_load_dwordx4 v[28:31], v[44:45], off offset:80
	s_nop 0
	global_load_dwordx4 v[44:47], v[44:45], off offset:64
	v_lshlrev_b32_e32 v57, 3, v54
	v_mul_lo_u32 v58, v51, s82
	v_lshlrev_b32_e32 v54, 4, v56
	v_mul_lo_u32 v56, v50, s83
	v_lshl_add_u32 v194, v55, 4, v58
	v_and_b32_e32 v55, 0x60, v54
	v_and_b32_e32 v57, 8, v57
	v_mad_u64_u32 v[184:185], s[0:1], v50, s82, v[54:55]
	v_add_u32_e32 v54, 0, v56
	v_add3_u32 v185, v54, v57, v55
	v_add_u32_e32 v56, 0, v194
	v_add_u32_e32 v54, 0xc800, v185
	v_add_u32_e32 v58, 0, v184
	v_add_u32_e32 v55, 0xe800, v185
	s_cmp_lt_i32 s4, 0
	s_mov_b32 s52, 0
	s_waitcnt vmcnt(0)
	ds_write_b128 v56, v[128:131]
	ds_write_b128 v56, v[132:135] offset:12800
	ds_write_b128 v58, v[136:139] offset:256
	ds_write2_b64 v54, v[140:141], v[142:143] offset1:2
	ds_write2_b64 v55, v[144:145], v[146:147] offset0:128 offset1:130
	v_mad_u32_u24 v54, v48, s83, 0
	v_add_u32_e32 v195, v54, v180
	v_add_u32_e32 v173, 0xc800, v195
	s_waitcnt lgkmcnt(0)
	s_barrier
	s_cbranch_scc1 .LBB0_1331
	v_lshlrev_b32_e32 v55, 8, v48
	v_add3_u32 v196, v54, v55, v180
	v_and_b32_e32 v55, 0xffff0000, v36
	v_lshlrev_b32_e32 v54, 16, v36
	v_and_b32_e32 v57, 0xffff0000, v32
	v_lshlrev_b32_e32 v56, 16, v32
	v_pk_mul_f32 v[58:59], v[44:45], v[56:57]
	v_pk_mul_f32 v[44:45], v[44:45], v[54:55]
	v_pk_fma_f32 v[58:59], v[40:41], v[54:55], v[58:59]
	v_pk_fma_f32 v[40:41], v[40:41], v[56:57], v[44:45] neg_lo:[0,0,1] neg_hi:[0,0,1]
	v_lshlrev_b32_e32 v36, 16, v33
	v_cvt_pk_bf16_f32 v152, v40, v41
	v_and_b32_e32 v41, 0xffff0000, v37
	v_lshlrev_b32_e32 v40, 16, v37
	v_and_b32_e32 v37, 0xffff0000, v33
	v_pk_mul_f32 v[32:33], v[46:47], v[36:37]
	s_lshl_b32 s53, s4, 2
	v_pk_fma_f32 v[32:33], v[42:43], v[40:41], v[32:33]
	v_mov_b32_e32 v200, 0
	v_cvt_pk_bf16_f32 v149, v32, v33
	v_pk_mul_f32 v[32:33], v[46:47], v[40:41]
	s_add_i32 s53, s53, 4
	v_pk_fma_f32 v[32:33], v[42:43], v[36:37], v[32:33] neg_lo:[0,0,1] neg_hi:[0,0,1]
	v_and_b32_e32 v37, 0xffff0000, v34
	v_cvt_pk_bf16_f32 v153, v32, v33
	v_and_b32_e32 v33, 0xffff0000, v38
	v_lshlrev_b32_e32 v32, 16, v38
	v_lshlrev_b32_e32 v36, 16, v34
	v_pk_mul_f32 v[40:41], v[28:29], v[36:37]
	v_pk_mul_f32 v[28:29], v[28:29], v[32:33]
	v_pk_fma_f32 v[40:41], v[24:25], v[32:33], v[40:41]
	v_pk_fma_f32 v[24:25], v[24:25], v[36:37], v[28:29] neg_lo:[0,0,1] neg_hi:[0,0,1]
	v_and_b32_e32 v29, 0xffff0000, v35
	v_lshlrev_b32_e32 v28, 16, v35
	v_cvt_pk_bf16_f32 v154, v24, v25
	v_and_b32_e32 v25, 0xffff0000, v39
	v_lshlrev_b32_e32 v24, 16, v39
	v_pk_mul_f32 v[32:33], v[30:31], v[28:29]
	v_cvt_pk_bf16_f32 v148, v58, v59
	v_pk_fma_f32 v[32:33], v[26:27], v[24:25], v[32:33]
	v_pk_mul_f32 v[24:25], v[30:31], v[24:25]
	v_cvt_pk_bf16_f32 v150, v40, v41
	v_pk_fma_f32 v[24:25], v[26:27], v[28:29], v[24:25] neg_lo:[0,0,1] neg_hi:[0,0,1]
	v_and_b32_e32 v27, 0xffff0000, v12
	v_cvt_pk_bf16_f32 v155, v24, v25
	v_and_b32_e32 v25, 0xffff0000, v16
	v_lshlrev_b32_e32 v24, 16, v16
	v_lshlrev_b32_e32 v26, 16, v12
	v_pk_mul_f32 v[28:29], v[20:21], v[26:27]
	v_pk_mul_f32 v[20:21], v[20:21], v[24:25]
	v_pk_fma_f32 v[28:29], v[4:5], v[24:25], v[28:29]
	v_pk_fma_f32 v[4:5], v[4:5], v[26:27], v[20:21] neg_lo:[0,0,1] neg_hi:[0,0,1]
	v_lshlrev_b32_e32 v16, 16, v13
	v_cvt_pk_bf16_f32 v160, v4, v5
	v_and_b32_e32 v5, 0xffff0000, v17
	v_lshlrev_b32_e32 v4, 16, v17
	v_and_b32_e32 v17, 0xffff0000, v13
	v_pk_mul_f32 v[12:13], v[22:23], v[16:17]
	v_cvt_pk_bf16_f32 v151, v32, v33
	v_pk_fma_f32 v[12:13], v[6:7], v[4:5], v[12:13]
	v_pk_mul_f32 v[4:5], v[22:23], v[4:5]
	v_cvt_pk_bf16_f32 v157, v12, v13
	v_pk_fma_f32 v[4:5], v[6:7], v[16:17], v[4:5] neg_lo:[0,0,1] neg_hi:[0,0,1]
	v_and_b32_e32 v7, 0xffff0000, v14
	v_lshlrev_b32_e32 v6, 16, v14
	v_cvt_pk_bf16_f32 v161, v4, v5
	v_and_b32_e32 v5, 0xffff0000, v18
	v_lshlrev_b32_e32 v4, 16, v18
	v_pk_mul_f32 v[12:13], v[8:9], v[6:7]
	v_cvt_pk_bf16_f32 v156, v28, v29
	v_pk_fma_f32 v[12:13], v[0:1], v[4:5], v[12:13]
	v_pk_mul_f32 v[4:5], v[8:9], v[4:5]
	v_cvt_pk_bf16_f32 v158, v12, v13
	v_pk_fma_f32 v[0:1], v[0:1], v[6:7], v[4:5] neg_lo:[0,0,1] neg_hi:[0,0,1]
	v_and_b32_e32 v5, 0xffff0000, v15
	v_lshlrev_b32_e32 v4, 16, v15
	v_cvt_pk_bf16_f32 v162, v0, v1
	v_and_b32_e32 v1, 0xffff0000, v19
	v_lshlrev_b32_e32 v0, 16, v19
	v_pk_mul_f32 v[6:7], v[10:11], v[4:5]
	v_mov_b32_e32 v199, 0xf149f2ca
	v_pk_fma_f32 v[6:7], v[2:3], v[0:1], v[6:7]
	v_pk_mul_f32 v[0:1], v[10:11], v[0:1]
	v_cvt_pk_bf16_f32 v159, v6, v7
	v_pk_fma_f32 v[0:1], v[2:3], v[4:5], v[0:1] neg_lo:[0,0,1] neg_hi:[0,0,1]
	s_mov_b32 s33, 63
	v_cvt_pk_bf16_f32 v163, v0, v1
	v_lshlrev_b32_e32 v1, 10, v51
	v_lshlrev_b32_e32 v0, 2, v49
	v_add3_u32 v186, s93, v1, v53
	v_add_u32_e32 v1, s97, v48
	v_sub_u32_e32 v197, v1, v0
	v_lshlrev_b32_e32 v0, 6, v50
	v_add3_u32 v188, s94, v0, v52
	v_lshlrev_b32_e32 v0, 15, v50
	v_add3_u32 v198, s95, v0, v52
	v_add_lshl_u32 v234, v50, s92, 11
	v_add_u32_e32 v198, v198, v234
	v_mov_b32_e32 v64, 0
	v_mov_b32_e32 v65, 0
	v_mov_b32_e32 v66, 0
	v_mov_b32_e32 v67, 0
	v_mov_b32_e32 v68, 0
	v_mov_b32_e32 v69, 0
	v_mov_b32_e32 v70, 0
	v_mov_b32_e32 v71, 0
	s_mov_b32 s0, 0
	v_mov_b32_e32 v0, 0
	v_mov_b32_e32 v1, v200
	v_mov_b32_e32 v2, v200
	v_mov_b32_e32 v3, v200
	v_mov_b32_e32 v4, v200
	v_mov_b32_e32 v5, v200
	v_mov_b32_e32 v6, v200
	v_mov_b32_e32 v7, v200
	v_mov_b32_e32 v8, v200
	v_mov_b32_e32 v9, v200
	v_mov_b32_e32 v10, v200
	v_mov_b32_e32 v11, v200
	v_mov_b32_e32 v12, v200
	v_mov_b32_e32 v13, v200
	v_mov_b32_e32 v14, v200
	v_mov_b32_e32 v15, v200
	v_mov_b32_e32 v16, 0
	v_mov_b32_e32 v17, v200
	v_mov_b32_e32 v18, v200
	v_mov_b32_e32 v19, v200
	v_mov_b32_e32 v20, v200
	v_mov_b32_e32 v21, v200
	v_mov_b32_e32 v22, v200
	v_mov_b32_e32 v23, v200
	v_mov_b32_e32 v24, v200
	v_mov_b32_e32 v25, v200
	v_mov_b32_e32 v26, v200
	v_mov_b32_e32 v27, v200
	v_mov_b32_e32 v28, v200
	v_mov_b32_e32 v29, v200
	v_mov_b32_e32 v30, v200
	v_mov_b32_e32 v31, v200
	v_mov_b32_e32 v32, 0
	v_mov_b32_e32 v33, v200
	v_mov_b32_e32 v34, v200
	v_mov_b32_e32 v35, v200
	v_mov_b32_e32 v36, v200
	v_mov_b32_e32 v37, v200
	v_mov_b32_e32 v38, v200
	v_mov_b32_e32 v39, v200
	v_mov_b32_e32 v40, v200
	v_mov_b32_e32 v41, v200
	v_mov_b32_e32 v42, v200
	v_mov_b32_e32 v43, v200
	v_mov_b32_e32 v44, v200
	v_mov_b32_e32 v45, v200
	v_mov_b32_e32 v46, v200
	v_mov_b32_e32 v47, v200
	v_mov_b32_e32 v48, 0
	v_mov_b32_e32 v49, v200
	v_mov_b32_e32 v50, v200
	v_mov_b32_e32 v51, v200
	v_mov_b32_e32 v52, v200
	v_mov_b32_e32 v53, v200
	v_mov_b32_e32 v54, v200
	v_mov_b32_e32 v55, v200
	v_mov_b32_e32 v56, v200
	v_mov_b32_e32 v57, v200
	v_mov_b32_e32 v58, v200
	v_mov_b32_e32 v59, v200
	v_mov_b32_e32 v60, v200
	v_mov_b32_e32 v61, v200
	v_mov_b32_e32 v62, v200
	v_mov_b32_e32 v63, v200
	v_mov_b32_e32 v187, 0
	v_mov_b32_e32 v189, 0
	s_mov_b32 s55, 0
	v_xor_b32_e32 v246, 32, v193
	v_lshlrev_b32_e32 v246, 2, v246
	v_mov_b32_e32 v64, 0xff61b1e6
	v_mov_b32_e32 v65, v64
	v_mov_b32_e32 v66, v64
	v_mov_b32_e32 v67, v64
	v_mov_b32_e32 v68, v64
	v_mov_b32_e32 v69, v64
	v_mov_b32_e32 v70, v64
	v_mov_b32_e32 v71, v64
	v_mov_b32_e32 v72, v64
	v_mov_b32_e32 v73, v64
	v_mov_b32_e32 v74, v64
	v_mov_b32_e32 v75, v64
	v_mov_b32_e32 v76, v64
	v_mov_b32_e32 v77, v64
	v_mov_b32_e32 v78, v64
	v_mov_b32_e32 v79, v64
	v_add_u32_e32 v201, 0xffff8000, v186
	v_lshlrev_b32_e32 v201, 1, v201
	v_lshlrev_b32_e32 v230, 1, v186
	v_lshlrev_b32_e32 v231, 1, v188
	v_add_u32_e32 v232, 64, v198
	v_lshlrev_b32_e32 v232, 1, v232
	v_add_u32_e32 v233, 0x440000, v232
	s_mov_b64 s[20:21], s[64:65]
	s_mov_b64 s[22:23], s[60:61]
	s_mov_b64 s[24:25], s[68:69]
	global_load_dwordx4 v[128:131], v201, s[20:21]
	global_load_dwordx4 v[132:135], v230, s[20:21]
	global_load_dwordx4 v[136:139], v231, s[22:23]
	global_load_dwordx4 v[140:143], v232, s[24:25]
	global_load_dwordx4 v[144:147], v233, s[24:25]
.LBB0_1340:
	s_add_i32 s54, s0, 1
	s_bitcmp1_b32 s0, 0
	s_cselect_b32 s4, 0x6400, 0
	v_add_u32_e32 v174, s4, v196
	s_mul_i32 s4, s52, 0x4800
	v_add_u32_e32 v234, s4, v195
	s_add_i32 s4, s97, 94
	s_cmp_gt_i32 s33, s4
	s_cbranch_scc1 .Lat_idle
	ds_read_b128 v[202:205], v174 offset:0
	ds_read_b128 v[206:209], v174 offset:32
	ds_read_b128 v[210:213], v174 offset:64
	ds_read_b128 v[214:217], v174 offset:96
	ds_read_b128 v[218:221], v174 offset:128
	ds_read_b128 v[222:225], v174 offset:160
	v_fma_f32 v64, v64, s84, -v199
	v_exp_f32_e32 v64, v64
	v_fma_f32 v65, v65, s84, -v199
	v_exp_f32_e32 v65, v65
	v_add_f32_e32 v200, v200, v64
	v_fma_f32 v66, v66, s84, -v199
	v_exp_f32_e32 v66, v66
	v_add_f32_e32 v200, v200, v65
	s_waitcnt lgkmcnt(4)
	v_mfma_f32_32x32x16_bf16 v[80:95], v[202:205], v[96:99], 0
	ds_read_b128 v[202:205], v174 offset:192
	v_fma_f32 v67, v67, s84, -v199
	v_exp_f32_e32 v67, v67
	v_add_f32_e32 v200, v200, v66
	v_fma_f32 v68, v68, s84, -v199
	v_mfma_f32_32x32x16_bf16 v[80:95], v[206:209], v[100:103], v[80:95]
	ds_read_b128 v[206:209], v174 offset:224
	v_exp_f32_e32 v68, v68
	v_add_f32_e32 v200, v200, v67
	v_fma_f32 v69, v69, s84, -v199
	v_exp_f32_e32 v69, v69
	s_waitcnt lgkmcnt(4)
	v_mfma_f32_32x32x16_bf16 v[80:95], v[210:213], v[104:107], v[80:95]
	ds_read_b128 v[210:213], v174 offset:256
	v_add_f32_e32 v200, v200, v68
	v_fma_f32 v70, v70, s84, -v199
	v_exp_f32_e32 v70, v70
	v_add_f32_e32 v200, v200, v69
	v_mfma_f32_32x32x16_bf16 v[80:95], v[214:217], v[108:111], v[80:95]
	ds_read_b128 v[214:217], v174 offset:288
	v_fma_f32 v71, v71, s84, -v199
	v_exp_f32_e32 v71, v71
	v_add_f32_e32 v200, v200, v70
	v_fma_f32 v72, v72, s84, -v199
	s_waitcnt lgkmcnt(4)
	v_mfma_f32_32x32x16_bf16 v[80:95], v[218:221], v[112:115], v[80:95]
	ds_read_b128 v[218:221], v174 offset:320
	v_exp_f32_e32 v72, v72
	v_add_f32_e32 v200, v200, v71
	v_fma_f32 v73, v73, s84, -v199
	v_exp_f32_e32 v73, v73
	v_mfma_f32_32x32x16_bf16 v[80:95], v[222:225], v[116:119], v[80:95]
	ds_read_b128 v[222:225], v174 offset:352
	v_add_f32_e32 v200, v200, v72
	v_fma_f32 v74, v74, s84, -v199
	v_exp_f32_e32 v74, v74
	v_add_f32_e32 v200, v200, v73
	s_waitcnt lgkmcnt(4)
	v_mfma_f32_32x32x16_bf16 v[80:95], v[202:205], v[120:123], v[80:95]
	ds_read_b128 v[164:167], v173 offset:0
	v_fma_f32 v75, v75, s84, -v199
	v_exp_f32_e32 v75, v75
	v_add_f32_e32 v200, v200, v74
	v_fma_f32 v76, v76, s84, -v199
	v_mfma_f32_32x32x16_bf16 v[80:95], v[206:209], v[124:127], v[80:95]
	ds_read_b128 v[168:171], v173 offset:4608
	v_exp_f32_e32 v76, v76
	v_add_f32_e32 v200, v200, v75
	v_fma_f32 v77, v77, s84, -v199
	v_exp_f32_e32 v77, v77
	s_waitcnt lgkmcnt(4)
	v_mfma_f32_32x32x16_bf16 v[80:95], v[210:213], v[160:163], v[80:95]
	ds_read_b128 v[176:179], v173 offset:9216
	v_add_f32_e32 v200, v200, v76
	v_fma_f32 v78, v78, s84, -v199
	v_exp_f32_e32 v78, v78
	v_add_f32_e32 v200, v200, v77
	v_mfma_f32_32x32x16_bf16 v[80:95], v[214:217], v[152:155], v[80:95]
	ds_read_b128 v[226:229], v173 offset:13824
	v_fma_f32 v79, v79, s84, -v199
	v_exp_f32_e32 v79, v79
	v_add_f32_e32 v200, v200, v78
	v_add_f32_e32 v200, v200, v79
	s_waitcnt lgkmcnt(4)
	v_mfma_f32_32x32x16_bf16 v[80:95], v[218:221], v[156:159], v[80:95]
	v_cvt_pk_bf16_f32 v64, v64, v65
	v_cvt_pk_bf16_f32 v65, v66, v67
	v_cvt_pk_bf16_f32 v66, v68, v69
	v_cvt_pk_bf16_f32 v67, v70, v71
	v_mfma_f32_32x32x16_bf16 v[80:95], v[222:225], v[148:151], v[80:95]
	v_cvt_pk_bf16_f32 v68, v72, v73
	v_cvt_pk_bf16_f32 v69, v74, v75
	v_cvt_pk_bf16_f32 v70, v76, v77
	v_cvt_pk_bf16_f32 v71, v78, v79
	s_waitcnt lgkmcnt(2)
	v_mfma_f32_32x32x16_bf16 v[48:63], v[164:167], v[64:67], v[48:63]
	ds_read_b128 v[164:167], v173 offset:32
	v_mfma_f32_32x32x16_bf16 v[32:47], v[168:171], v[64:67], v[32:47]
	ds_read_b128 v[168:171], v173 offset:4640
	s_waitcnt lgkmcnt(2)
	v_mfma_f32_32x32x16_bf16 v[16:31], v[176:179], v[64:67], v[16:31]
	ds_read_b128 v[176:179], v173 offset:9248
	v_mfma_f32_32x32x16_bf16 v[0:15], v[226:229], v[64:67], v[0:15]
	ds_read_b128 v[226:229], v173 offset:13856
	ds_read_b128 v[202:205], v174 offset:12800
	ds_read_b128 v[206:209], v174 offset:12832
	ds_read_b128 v[210:213], v174 offset:12864
	ds_read_b128 v[214:217], v174 offset:12896
	ds_read_b128 v[218:221], v174 offset:12928
	ds_read_b128 v[222:225], v174 offset:12960
	s_cmp_gt_i32 s33, s97
	s_cbranch_scc1 .Lat_mask_a

.Lat_idle:
	s_cmp_lg_u32 s55, 0
	s_cbranch_scc1 .Lat_idle_go
	s_mov_b32 s55, 1
	v_fma_f32 v64, v64, s84, -v199
	v_exp_f32_e32 v64, v64
	v_fma_f32 v65, v65, s84, -v199
	v_exp_f32_e32 v65, v65
	v_add_f32_e32 v200, v200, v64
	v_fma_f32 v66, v66, s84, -v199
	v_exp_f32_e32 v66, v66
	v_add_f32_e32 v200, v200, v65
	v_fma_f32 v67, v67, s84, -v199
	v_exp_f32_e32 v67, v67
	v_add_f32_e32 v200, v200, v66
	v_fma_f32 v68, v68, s84, -v199
	v_exp_f32_e32 v68, v68
	v_add_f32_e32 v200, v200, v67
	v_fma_f32 v69, v69, s84, -v199
	v_exp_f32_e32 v69, v69
	v_add_f32_e32 v200, v200, v68
	v_fma_f32 v70, v70, s84, -v199
	v_exp_f32_e32 v70, v70
	v_add_f32_e32 v200, v200, v69
	v_fma_f32 v71, v71, s84, -v199
	v_exp_f32_e32 v71, v71
	v_add_f32_e32 v200, v200, v70
	v_fma_f32 v72, v72, s84, -v199
	v_exp_f32_e32 v72, v72
	v_add_f32_e32 v200, v200, v71
	v_fma_f32 v73, v73, s84, -v199
	v_exp_f32_e32 v73, v73
	v_add_f32_e32 v200, v200, v72
	v_fma_f32 v74, v74, s84, -v199
	v_exp_f32_e32 v74, v74
	v_add_f32_e32 v200, v200, v73
	v_fma_f32 v75, v75, s84, -v199
	v_exp_f32_e32 v75, v75
	v_add_f32_e32 v200, v200, v74
	v_fma_f32 v76, v76, s84, -v199
	v_exp_f32_e32 v76, v76
	v_add_f32_e32 v200, v200, v75
	v_fma_f32 v77, v77, s84, -v199
	v_exp_f32_e32 v77, v77
	v_add_f32_e32 v200, v200, v76
	v_fma_f32 v78, v78, s84, -v199
	v_exp_f32_e32 v78, v78
	v_add_f32_e32 v200, v200, v77
	v_fma_f32 v79, v79, s84, -v199
	v_exp_f32_e32 v79, v79
	v_add_f32_e32 v200, v200, v78
	v_add_f32_e32 v200, v200, v79
	v_cvt_pk_bf16_f32 v64, v64, v65
	v_cvt_pk_bf16_f32 v65, v66, v67
	v_cvt_pk_bf16_f32 v66, v68, v69
	v_cvt_pk_bf16_f32 v67, v70, v71
	v_cvt_pk_bf16_f32 v68, v72, v73
	v_cvt_pk_bf16_f32 v69, v74, v75
	v_cvt_pk_bf16_f32 v70, v76, v77
	v_cvt_pk_bf16_f32 v71, v78, v79
	ds_read_b128 v[164:167], v173 offset:0
	ds_read_b128 v[168:171], v173 offset:4608
	ds_read_b128 v[176:179], v173 offset:9216
	ds_read_b128 v[226:229], v173 offset:13824
	s_waitcnt lgkmcnt(0)
	v_mfma_f32_32x32x16_bf16 v[48:63], v[164:167], v[64:67], v[48:63]
	v_mfma_f32_32x32x16_bf16 v[32:47], v[168:171], v[64:67], v[32:47]
	v_mfma_f32_32x32x16_bf16 v[16:31], v[176:179], v[64:67], v[16:31]
	v_mfma_f32_32x32x16_bf16 v[0:15], v[226:229], v[64:67], v[0:15]
	ds_read_b128 v[164:167], v173 offset:32
	ds_read_b128 v[168:171], v173 offset:4640
	ds_read_b128 v[176:179], v173 offset:9248
	ds_read_b128 v[226:229], v173 offset:13856
	s_waitcnt lgkmcnt(0)
	v_mfma_f32_32x32x16_bf16 v[48:63], v[164:167], v[68:71], v[48:63]
	v_mfma_f32_32x32x16_bf16 v[32:47], v[168:171], v[68:71], v[32:47]
	v_mfma_f32_32x32x16_bf16 v[16:31], v[176:179], v[68:71], v[16:31]
	v_mfma_f32_32x32x16_bf16 v[0:15], v[226:229], v[68:71], v[0:15]
	s_nop 7
	v_mov_b32_e32 v64, 0xff61b1e6
	v_mov_b32_e32 v65, v64
	v_mov_b32_e32 v66, v64
	v_mov_b32_e32 v67, v64
	v_mov_b32_e32 v68, v64
	v_mov_b32_e32 v69, v64
	v_mov_b32_e32 v70, v64
	v_mov_b32_e32 v71, v64
	v_mov_b32_e32 v72, v64
	v_mov_b32_e32 v73, v64
	v_mov_b32_e32 v74, v64
	v_mov_b32_e32 v75, v64
	v_mov_b32_e32 v76, v64
	v_mov_b32_e32 v77, v64
	v_mov_b32_e32 v78, v64
	v_mov_b32_e32 v79, v64
.Lat_idle_go:
	s_branch .Lat_resc_b_ret
